# nt policy on the final output stores (written once, never re-read in the launch)
# speedup vs baseline: 1.0283x; 1.0034x over previous
.LBB0_79:
	v_ashrrev_i32_e32 v7, 31, v6
	v_lshlrev_b64 v[12:13], 7, v[6:7]
	v_lshl_add_u64 v[40:41], s[16:17], 0, v[12:13]
	global_load_dwordx4 v[12:15], v[40:41], off offset:48
	global_load_dwordx4 v[16:19], v[40:41], off offset:32
	global_load_dwordx4 v[20:23], v[40:41], off
	global_load_dwordx4 v[24:27], v[40:41], off offset:16
	global_load_dwordx4 v[28:31], v[40:41], off offset:112
	global_load_dwordx4 v[32:35], v[40:41], off offset:96
	global_load_dwordx4 v[36:39], v[40:41], off offset:80
	s_nop 0
	global_load_dwordx4 v[40:43], v[40:41], off offset:64
	v_lshlrev_b64 v[8:9], 12, v[6:7]
	v_lshl_add_u64 v[10:11], v[2:3], 0, v[8:9]
	s_add_i32 s2, s2, s70
	v_add_u32_e32 v6, s3, v6
	s_cmpk_gt_i32 s2, 0x7ff
	s_waitcnt vmcnt(0)
	v_add_f32_e32 v12, v12, v13
	v_add_f32_e32 v14, v14, v15
	s_waitcnt vmcnt(5)
	v_mov_b32_e32 v44, v20
	s_waitcnt vmcnt(4)
	v_mov_b32_e32 v45, v24
	v_mov_b32_e32 v24, v21
	v_pk_add_f32 v[20:21], v[44:45], v[24:25]
	v_mov_b32_e32 v24, v22
	v_mov_b32_e32 v25, v26
	v_mov_b32_e32 v26, v23
	v_pk_add_f32 v[22:23], v[24:25], v[26:27]
	s_waitcnt vmcnt(0)
	v_mov_b32_e32 v13, v42
	v_pk_add_f32 v[20:21], v[20:21], v[22:23]
	v_mov_b32_e32 v22, v17
	v_mov_b32_e32 v23, v18
	v_mov_b32_e32 v17, v19
	v_pk_add_f32 v[16:17], v[22:23], v[16:17]
	v_add_f32_e32 v7, 0, v20
	v_pk_add_f32 v[16:17], v[16:17], v[16:17] op_sel:[0,1] op_sel_hi:[1,0]
	v_add_f32_e32 v20, v7, v21
	v_mov_b32_e32 v21, v40
	v_mov_b32_e32 v17, v41
	v_mov_b32_e32 v15, v43
	v_pk_add_f32 v[16:17], v[20:21], v[16:17]
	v_pk_add_f32 v[12:13], v[12:13], v[14:15]
	v_mov_b32_e32 v14, v37
	v_mov_b32_e32 v15, v38
	v_mov_b32_e32 v37, v39
	v_pk_add_f32 v[12:13], v[16:17], v[12:13]
	v_pk_add_f32 v[14:15], v[14:15], v[36:37]
	v_pk_add_f32 v[12:13], v[12:13], v[12:13] op_sel:[0,1] op_sel_hi:[1,0]
	v_pk_add_f32 v[14:15], v[14:15], v[14:15] op_sel:[0,1] op_sel_hi:[1,0]
	v_add_f32_e32 v16, v32, v33
	v_add_f32_e32 v18, v34, v35
	v_mov_b32_e32 v13, v28
	v_mov_b32_e32 v15, v29
	v_mov_b32_e32 v17, v30
	v_mov_b32_e32 v19, v31
	v_pk_add_f32 v[12:13], v[12:13], v[14:15]
	v_pk_add_f32 v[14:15], v[16:17], v[18:19]
	s_nop 0
	v_pk_add_f32 v[12:13], v[12:13], v[14:15]
	s_nop 0
	v_add_f32_e32 v7, v12, v13
	v_fmamk_f32 v7, v7, 0x3a800000, v250
	v_cmp_gt_f32_e32 vcc, s94, v7
	v_mul_f32_e32 v12, 0x4b800000, v7
	s_nop 0
	v_cndmask_b32_e32 v7, v7, v12, vcc
	global_load_dwordx4 v[12:15], v[10:11], off
	global_load_dwordx4 v[16:19], v[0:1], off
	global_load_dwordx4 v[20:23], v[10:11], off offset:1024
	global_load_dwordx4 v[24:27], v[0:1], off offset:1024
	global_load_dwordx4 v[28:31], v[10:11], off offset:2048
	global_load_dwordx4 v[32:35], v[0:1], off offset:2048
	global_load_dwordx4 v[36:39], v[10:11], off offset:3072
	global_load_dwordx4 v[40:43], v[0:1], off offset:3072
	v_rsq_f32_e32 v7, v7
	s_waitcnt vmcnt(7)
	v_mul_f32_e32 v44, 0x45800000, v7
	v_cndmask_b32_e32 v44, v7, v44, vcc
	v_pk_mul_f32 v[10:11], v[12:13], v[44:45] op_sel_hi:[1,0]
	v_pk_mul_f32 v[12:13], v[14:15], v[44:45] op_sel_hi:[1,0]
	s_waitcnt vmcnt(6)
	v_lshl_add_u64 v[14:15], v[4:5], 0, v[8:9]
	v_pk_mul_f32 v[12:13], v[18:19], v[12:13]
	v_pk_mul_f32 v[10:11], v[16:17], v[10:11]
	s_waitcnt vmcnt(5)
	s_waitcnt vmcnt(4)
	s_waitcnt vmcnt(3)
	s_waitcnt vmcnt(2)
	s_waitcnt vmcnt(1)
	s_waitcnt vmcnt(0)
	global_store_dwordx4 v[14:15], v[10:13], off nt
	v_pk_mul_f32 v[8:9], v[20:21], v[44:45] op_sel_hi:[1,0]
	s_nop 0
	v_pk_mul_f32 v[10:11], v[22:23], v[44:45] op_sel_hi:[1,0]
	v_pk_mul_f32 v[8:9], v[24:25], v[8:9]
	v_pk_mul_f32 v[10:11], v[26:27], v[10:11]
	global_store_dwordx4 v[14:15], v[8:11], off offset:1024 nt
	s_nop 1
	v_pk_mul_f32 v[8:9], v[28:29], v[44:45] op_sel_hi:[1,0]
	v_pk_mul_f32 v[10:11], v[30:31], v[44:45] op_sel_hi:[1,0]
	v_pk_mul_f32 v[8:9], v[32:33], v[8:9]
	v_pk_mul_f32 v[10:11], v[34:35], v[10:11]
	global_store_dwordx4 v[14:15], v[8:11], off offset:2048 nt
	s_nop 1
	v_pk_mul_f32 v[8:9], v[36:37], v[44:45] op_sel_hi:[1,0]
	v_pk_mul_f32 v[10:11], v[38:39], v[44:45] op_sel_hi:[1,0]
	v_pk_mul_f32 v[8:9], v[40:41], v[8:9]
	v_pk_mul_f32 v[10:11], v[42:43], v[10:11]
	global_store_dwordx4 v[14:15], v[8:11], off offset:3072 nt
	s_cbranch_scc0 .LBB0_79
